# FFN prenorm: rows iterated last to first as well (context rows with partial sums first); next-row prefetch adapted to the descending order
# baseline (speedup 1.0000x reference)
.LBB0_199:
	s_ashr_i32 s5, s3, 6
	s_add_i32 s10, s5, s40
	s_cmp_ge_i32 s10, s28
	s_cbranch_scc1 .LBB0_218
	v_readlane_b32 s6, v255, 14
	v_readlane_b32 s7, v255, 15
	s_load_dwordx2 s[12:13], s[6:7], 0x0
	s_nop 0
	s_load_dwordx2 s[6:7], s[0:1], 0xc8
	v_lshlrev_b32_e32 v0, 2, v2
	v_and_b32_e32 v66, 0xfc, v0
	v_lshlrev_b32_e32 v0, 2, v66
	v_and_b32_e32 v3, 64, v228
	s_waitcnt lgkmcnt(0)
	s_add_u32 s3, s6, 0x103000
	s_addc_u32 s4, s7, 0
	v_lshl_add_u64 v[4:5], s[6:7], 0, v[0:1]
	s_mov_b64 s[6:7], 0xbb00000
	v_lshl_add_u64 v[68:69], v[4:5], 0, s[6:7]
	v_add_u32_e32 v3, 64, v3
	v_xor_b32_e32 v4, 1, v228
	v_cmp_lt_i32_e32 vcc, v4, v3
	v_readlane_b32 s6, v255, 52
	v_readlane_b32 s7, v255, 53
	v_cndmask_b32_e32 v4, v228, v4, vcc
	v_lshlrev_b32_e32 v67, 2, v4
	v_xor_b32_e32 v4, 2, v228
	v_cmp_lt_i32_e32 vcc, v4, v3
	v_lshl_add_u64 v[76:77], s[6:7], 0, v[0:1]
	v_readlane_b32 s6, v254, 46
	v_cndmask_b32_e32 v4, v228, v4, vcc
	v_lshlrev_b32_e32 v71, 2, v4
	v_xor_b32_e32 v4, 4, v228
	v_cmp_lt_i32_e32 vcc, v4, v3
	s_ashr_i32 s11, s10, 31
	s_add_i32 s74, s6, s5
	v_cndmask_b32_e32 v4, v228, v4, vcc
	v_lshlrev_b32_e32 v73, 2, v4
	v_xor_b32_e32 v4, 8, v228
	v_cmp_lt_i32_e32 vcc, v4, v3
	s_lshl_b64 s[6:7], s[10:11], 11
	v_readlane_b32 s5, v255, 54
	v_cndmask_b32_e32 v4, v228, v4, vcc
	v_lshlrev_b32_e32 v75, 2, v4
	v_xor_b32_e32 v4, 16, v228
	v_cmp_lt_i32_e32 vcc, v4, v3
	v_and_b32_e32 v0, 63, v2
	s_add_u32 s6, s5, s6
	v_cndmask_b32_e32 v4, v228, v4, vcc
	v_lshlrev_b32_e32 v80, 2, v4
	v_xor_b32_e32 v4, 32, v228
	v_cmp_lt_i32_e32 vcc, v4, v3
	v_readlane_b32 s5, v255, 55
	v_lshlrev_b32_e32 v0, 3, v0
	v_cndmask_b32_e32 v3, v228, v4, vcc
	s_addc_u32 s7, s5, s7
	v_or_b32_e32 v70, 0x100, v66
	v_or_b32_e32 v72, 0x200, v66
	v_or_b32_e32 v74, 0x300, v66
	v_lshlrev_b32_e32 v81, 2, v3
	v_lshl_add_u64 v[78:79], s[6:7], 0, v[0:1]
	v_lshlrev_b32_e32 v0, 2, v66
	s_mov_b32 s16, 0
.Lpn1rev_fwd:
	s_add_i32 s5, s74, s26
	s_add_i32 s5, s5, 0x4000
	s_cmp_ge_i32 s5, s28
	s_cbranch_scc1 .Lpn1rev_done
	s_add_i32 s74, s74, s26
	s_add_u32 s10, s10, s26
	s_addc_u32 s11, s11, s27
	s_add_i32 s16, s16, 1
	s_branch .Lpn1rev_fwd
.Lpn1rev_done:
	v_readlane_b32 s6, v254, 60
	v_readlane_b32 s7, v254, 61
	s_nop 0
	s_mul_i32 s5, s16, s7
	s_mul_hi_u32 s7, s16, s6
	s_add_i32 s7, s7, s5
	s_mul_i32 s6, s16, s6
	s_nop 0
	v_lshl_add_u64 v[78:79], v[78:79], 0, s[6:7]
	s_mov_b32 s100, 0
	s_branch .LBB0_202
.LBB0_201:
	s_sub_i32 s74, s74, s26
	s_sub_u32 s10, s10, s26
	v_readlane_b32 s6, v254, 60
	s_subb_u32 s11, s11, s27
	s_add_i32 s5, s74, 0x4000
	v_readlane_b32 s7, v254, 61
	s_nop 0
	s_sub_u32 s6, 0, s6
	s_subb_u32 s7, 0, s7
	s_cmp_lt_i32 s5, 0
	s_nop 0
	v_lshl_add_u64 v[78:79], v[78:79], 0, s[6:7]
	s_cbranch_scc1 .LBB0_218

.LBB0_210:
	s_nop 0
	v_pk_mul_f32 v[140:141], v[48:49], v[48:49]
	s_nop 0
	v_pk_mul_f32 v[142:143], v[46:47], v[46:47]
	v_pk_mul_f32 v[130:131], v[8:9], v[8:9]
	v_pk_mul_f32 v[132:133], v[6:7], v[6:7]
	v_pk_mov_b32 v[144:145], v[142:143], v[140:141] op_sel:[1,0]
	v_mov_b32_e32 v143, v141
	v_pk_add_f32 v[140:141], v[144:145], v[142:143]
	v_pk_mov_b32 v[142:143], v[132:133], v[130:131] op_sel:[1,0]
	v_mov_b32_e32 v133, v131
	s_min_i32 s6, s17, 0x4000
	v_pk_mul_f32 v[134:135], v[4:5], v[4:5]
	v_pk_mul_f32 v[136:137], v[2:3], v[2:3]
	v_pk_add_f32 v[130:131], v[142:143], v[132:133]
	s_ashr_i32 s6, s6, 12
	v_readlane_b32 s17, v255, 30
	s_min_i32 s5, s5, 0x4000
	v_pk_mov_b32 v[138:139], v[136:137], v[134:135] op_sel:[1,0]
	v_mov_b32_e32 v137, v135
	v_pk_add_f32 v[130:131], v[130:131], v[130:131] op_sel_hi:[0,1]
	s_add_i32 s6, s6, s17
	s_ashr_i32 s5, s5, 12
	v_pk_add_f32 v[134:135], v[138:139], v[136:137]
	v_pk_mul_f32 v[136:137], v[44:45], v[44:45]
	v_pk_mul_f32 v[138:139], v[42:43], v[42:43]
	v_mul_f32_e32 v130, v10, v10
	s_mulk_i32 s6, 0x1800
	s_add_i32 s5, s5, s17
	v_pk_mov_b32 v[132:133], v[138:139], v[136:137] op_sel:[1,0]
	v_mov_b32_e32 v139, v137
	v_pk_fma_f32 v[136:137], v[10:11], v[10:11], v[130:131] op_sel_hi:[1,1,0]
	v_mul_f32_e32 v130, v12, v12
	s_ashr_i32 s7, s6, 31
	s_mul_i32 s18, s5, 0x1800
	v_pk_add_f32 v[132:133], v[132:133], v[138:139]
	v_pk_fma_f32 v[138:139], v[12:13], v[12:13], v[130:131] op_sel_hi:[1,1,0]
	v_mul_f32_e32 v130, v38, v38
	s_ashr_i32 s19, s18, 31
	s_lshl_b64 s[6:7], s[6:7], 2
	v_pk_fma_f32 v[142:143], v[38:39], v[38:39], v[130:131] op_sel_hi:[1,1,0]
	v_mul_f32_e32 v130, v40, v40
	s_add_u32 s20, s3, s6
	v_pk_add_f32 v[134:135], v[134:135], v[134:135] op_sel_hi:[0,1]
	v_pk_add_f32 v[140:141], v[140:141], v[140:141] op_sel_hi:[0,1]
	v_pk_add_f32 v[132:133], v[132:133], v[132:133] op_sel_hi:[0,1]
	v_pk_fma_f32 v[144:145], v[40:41], v[40:41], v[130:131] op_sel_hi:[1,1,0]
	s_addc_u32 s21, s4, s7
	s_lshl_b64 s[6:7], s[18:19], 2
	v_mul_f32_e32 v136, v14, v14
	v_mul_f32_e32 v138, v15, v15
	v_mul_f32_e32 v134, v16, v16
	v_mul_f32_e32 v130, v17, v17
	v_mul_f32_e32 v142, v34, v34
	v_mul_f32_e32 v144, v35, v35
	v_mul_f32_e32 v140, v36, v36
	v_mul_f32_e32 v132, v37, v37
	s_add_u32 s18, s3, s6
	v_pk_add_f32 v[136:137], v[136:137], v[138:139]
	v_pk_add_f32 v[130:131], v[134:135], v[130:131]
	v_pk_add_f32 v[134:135], v[142:143], v[144:145]
	v_pk_add_f32 v[132:133], v[140:141], v[132:133]
	s_addc_u32 s19, s4, s7
	v_pk_add_f32 v[130:131], v[136:137], v[130:131]
	v_pk_add_f32 v[132:133], v[134:135], v[132:133]
	v_mov_b32_e32 v135, v130
	v_mov_b32_e32 v134, v132
	v_mov_b32_e32 v130, v133
	s_add_u32 s24, s20, 0x1000
	v_pk_add_f32 v[130:131], v[134:135], v[130:131]
	s_addc_u32 s25, s21, 0
	global_load_dwordx4 v[134:137], v0, s[20:21]
	global_load_dwordx4 v[138:141], v0, s[24:25]
	s_add_u32 s22, s18, 0x1000
	s_addc_u32 s23, s19, 0
	global_load_dwordx4 v[82:85], v0, s[20:21] offset:1024
	global_load_dwordx4 v[86:89], v0, s[24:25] offset:1024
	global_load_dwordx4 v[90:93], v0, s[20:21] offset:2048
	global_load_dwordx4 v[94:97], v0, s[24:25] offset:2048
	global_load_dwordx4 v[98:101], v0, s[20:21] offset:3072
	global_load_dwordx4 v[102:105], v0, s[24:25] offset:3072
	global_load_dwordx4 v[106:109], v0, s[18:19]
	global_load_dwordx4 v[110:113], v0, s[22:23]
	global_load_dwordx4 v[114:117], v0, s[18:19] offset:1024
	global_load_dwordx4 v[118:121], v0, s[22:23] offset:1024
	global_load_dwordx4 v[122:125], v0, s[18:19] offset:2048
	global_load_dwordx4 v[126:129], v0, s[22:23] offset:2048
	global_load_dwordx4 v[146:149], v0, s[18:19] offset:3072
	global_load_dwordx4 v[150:153], v0, s[22:23] offset:3072
	s_cmpk_lt_i32 s16, 0x4000
	s_cbranch_scc0 .Lpn1_nopf
	s_sub_i32 s6, s16, s26
	s_sub_i32 s6, s6, s42
	s_cmp_lt_i32 s6, 0
	s_cbranch_scc1 .Lpn1_nopf
	s_lshl_b32 s6, s26, 12
	s_sub_u32 s18, s100, s6
	s_subb_u32 s19, s101, 0
	s_lshl_b32 s6, s42, 12
	s_add_u32 s20, s18, s6
	s_addc_u32 s21, s19, 0
	global_load_dwordx4 v[18:21], v0, s[18:19] nt
	global_load_dwordx4 v[22:25], v0, s[18:19] offset:1024 nt
	global_load_dwordx4 v[62:65], v0, s[20:21] nt
	global_load_dwordx4 v[54:57], v0, s[20:21] offset:1024 nt
	global_load_dwordx4 v[26:29], v0, s[18:19] offset:2048 nt
	global_load_dwordx4 v[30:33], v0, s[18:19] offset:3072 nt
	global_load_dwordx4 v[58:61], v0, s[20:21] offset:2048 nt
	global_load_dwordx4 v[50:53], v0, s[20:21] offset:3072 nt
	s_mov_b32 s100, 1
